# attA steady tiles: no row-max work unless the tile may be skippable (chain-0 max derived in the rare path from the exponentiated values), one-op prediction bookkeeping; attB: packed O-rescale multipli
# baseline (speedup 1.0000x reference)
; __device__ __forceinline__ unsigned cvtpk(float lo, float hi) { return pg8::cvt_pk_bf16(lo, hi); }
; __device__ __forceinline__ float ex2(float v) { return __builtin_amdgcn_exp2f(v); }
; #define MFMA32(a, b, c) __builtin_amdgcn_mfma_f32_32x32x16_bf16((a), (b), (c), 0, 0, 0)
; __device__ __forceinline__ void unit(LAS unsigned char* lds, bf16_t* P1, int b, int h, int chunk) {
;     ...
;                 const float tb = sd * (float)(ib - iq);
;                 float mx = S[0];
; #pragma unroll
;                 for (int r = 1; r < 16; ++r) mx = fmaxf(mx, S[r]);
;                 float mt = mx + tb; mt = fmaxf(mt, __shfl_xor(mt, 32));
;                 const float mn = fmaxf(m, mt); const float alpha = ex2(m - mn); m = mn; const float c = tb - mn;
;                 float ps = 0.f;
; #pragma unroll
;                 for (int r = 0; r < 16; ++r) { S[r] = ex2(S[r] + c); ps += S[r]; }
;                 l = l * alpha + ps; O[0] = O[0] * alpha; O[1] = O[1] * alpha;
;                 u32x4 pk[2];
; #pragma unroll
;                 for (int s = 0; s < 2; ++s) pk[s] = (u32x4){cvtpk(S[8 * s + 0], S[8 * s + 1]), cvtpk(S[8 * s + 2], S[8 * s + 3]), cvtpk(S[8 * s + 4], S[8 * s + 5]), cvtpk(S[8 * s + 6], S[8 * s + 7])};
; #pragma unroll
;                 for (int d = 0; d < 2; ++d)
; #pragma unroll
;                     for (int s = 0; s < 2; ++s) O[d] = MFMA32(vfr[2 * d + s], __builtin_bit_cast(bf16x8, pk[s]), O[d]);
.LBB0_321:
	s_nop 7
	v_max_f32_e32 v174, v49, v49
	v_max_f32_e32 v175, v48, v48
	v_max_f32_e32 v174, v175, v174
	v_max3_f32 v174, v174, v50, v51
	v_max3_f32 v174, v174, v52, v53
	v_add_u32_e32 v173, s4, v139
	v_max3_f32 v174, v174, v54, v55
	v_cvt_f32_i32_e32 v173, v173
	v_max3_f32 v174, v174, v56, v57
	v_max3_f32 v174, v174, v58, v59
	v_max3_f32 v174, v174, v60, v61
	v_max3_f32 v174, v174, v62, v63
	v_fmac_f32_e32 v174, v122, v173
	ds_bpermute_b32 v175, v115, v174
	s_waitcnt lgkmcnt(0)
	v_max3_f32 v174, v117, v174, v175
	v_fma_f32 v173, v122, v173, -v174
	v_add_f32_e32 v48, v48, v173
	v_exp_f32_e32 v48, v48
	v_add_f32_e32 v49, v49, v173
	v_add_f32_e32 v50, v50, v173
	v_exp_f32_e32 v49, v49
	v_exp_f32_e32 v50, v50
	v_add_f32_e32 v51, v51, v173
	v_exp_f32_e32 v51, v51
	v_add_f32_e32 v52, v52, v173
	v_add_f32_e32 v175, 0, v48
	v_exp_f32_e32 v52, v52
	v_add_f32_e32 v53, v53, v173
	v_add_f32_e32 v175, v49, v175
	v_exp_f32_e32 v53, v53
	v_add_f32_e32 v54, v54, v173
	v_add_f32_e32 v175, v50, v175
	v_exp_f32_e32 v54, v54
	v_add_f32_e32 v55, v55, v173
	v_add_f32_e32 v175, v51, v175
	v_exp_f32_e32 v55, v55
	v_add_f32_e32 v56, v56, v173
	v_add_f32_e32 v175, v52, v175
	v_exp_f32_e32 v56, v56
	v_add_f32_e32 v57, v57, v173
	v_add_f32_e32 v175, v53, v175
	v_exp_f32_e32 v57, v57
	v_add_f32_e32 v58, v58, v173
	v_add_f32_e32 v175, v54, v175
	v_exp_f32_e32 v58, v58
	v_add_f32_e32 v59, v59, v173
	v_add_f32_e32 v175, v55, v175
	v_exp_f32_e32 v59, v59
	v_add_f32_e32 v60, v60, v173
	v_add_f32_e32 v175, v56, v175
	v_exp_f32_e32 v177, v60
	v_add_f32_e32 v60, v57, v175
	v_add_f32_e32 v60, v58, v60
	v_add_f32_e32 v60, v59, v60
	v_sub_f32_e32 v117, v117, v174
	v_add_f32_e32 v175, v177, v60
	v_add_f32_e32 v60, v61, v173
	v_exp_f32_e32 v61, v60
	v_exp_f32_e32 v60, v117
	v_cvt_pk_bf16_f32 v48, v48, v49
	v_cvt_pk_bf16_f32 v49, v50, v51
	v_cvt_pk_bf16_f32 v50, v52, v53
	v_cvt_pk_bf16_f32 v51, v54, v55
	s_waitcnt vmcnt(20)
	v_perm_b32 v55, v168, v167, s46
	v_perm_b32 v54, v166, v165, s46
	v_perm_b32 v53, v159, v156, s46
	v_perm_b32 v52, v154, v153, s46
	v_mul_f32_e32 v46, v60, v46
	v_mul_f32_e32 v47, v60, v47
	v_mul_f32_e32 v44, v60, v44
	v_mul_f32_e32 v45, v60, v45
	v_mul_f32_e32 v42, v60, v42
	v_mul_f32_e32 v43, v60, v43
	v_mul_f32_e32 v40, v60, v40
	v_mul_f32_e32 v41, v60, v41
	v_mul_f32_e32 v38, v60, v38
	v_mul_f32_e32 v39, v60, v39
	v_mul_f32_e32 v36, v60, v36
	v_mul_f32_e32 v37, v60, v37
	v_mul_f32_e32 v34, v60, v34
	v_mul_f32_e32 v35, v60, v35
	v_mul_f32_e32 v32, v60, v32
	v_mul_f32_e32 v33, v60, v33
	v_add_f32_e32 v62, v62, v173
	v_add_f32_e32 v63, v63, v173
	v_mfma_f32_32x32x16_bf16 v[32:47], v[52:55], v[48:51], v[32:47]
	v_exp_f32_e32 v62, v62
	v_exp_f32_e32 v63, v63
	s_waitcnt vmcnt(4)
	v_perm_b32 v55, v172, v171, s46
	v_perm_b32 v54, v170, v169, s46
	v_perm_b32 v53, v164, v163, s46
	v_perm_b32 v52, v162, v161, s46
	v_cvt_pk_bf16_f32 v56, v56, v57
	v_cvt_pk_bf16_f32 v57, v58, v59
	v_cvt_pk_bf16_f32 v58, v177, v61
	v_cvt_pk_bf16_f32 v59, v62, v63
	v_mul_f32_e32 v30, v60, v30
	v_mul_f32_e32 v31, v60, v31
	v_mul_f32_e32 v28, v60, v28
	v_mul_f32_e32 v29, v60, v29
	v_mfma_f32_32x32x16_bf16 v[32:47], v[52:55], v[56:59], v[32:47]
	v_perm_b32 v55, v149, v151, s46
	v_perm_b32 v54, v150, v152, s46
	v_perm_b32 v53, v119, v143, s46
	v_perm_b32 v52, v127, v144, s46
	v_mul_f32_e64 v26, v26, v60
	v_mul_f32_e64 v27, v27, v60
	v_mul_f32_e32 v24, v60, v24
	v_mul_f32_e32 v25, v60, v25
	v_mul_f32_e32 v22, v60, v22
	v_mul_f32_e32 v23, v60, v23
	v_mul_f32_e32 v20, v60, v20
	v_mul_f32_e32 v21, v60, v21
	v_mul_f32_e32 v18, v60, v18
	v_mul_f32_e32 v19, v60, v19
	v_mul_f32_e32 v16, v60, v16
	v_mul_f32_e32 v17, v60, v17
	v_mov_b32_e32 v117, v174
	s_nop 0
	v_mfma_f32_32x32x16_bf16 v[16:31], v[52:55], v[48:51], v[16:31]
	s_waitcnt vmcnt(2)
	v_perm_b32 v51, v155, v158, s46
	s_waitcnt vmcnt(0)
	v_perm_b32 v50, v157, v160, s46
	v_perm_b32 v49, v145, v147, s46
	v_perm_b32 v48, v146, v148, s46
	v_add_f32_e32 v52, v61, v175
	v_add_f32_e32 v52, v62, v52
	v_add_f32_e32 v52, v63, v52
	v_mfma_f32_32x32x16_bf16 v[16:31], v[48:51], v[56:59], v[16:31]
	v_fmac_f32_e32 v52, v113, v60
	v_mov_b32_e32 v113, v52

; #define LAS __attribute__((address_space(3)))
; __device__ __forceinline__ void unit(LAS unsigned char* lds, bf16_t* P1, const bf16_t* vaT, int b, int h, int qblk, float lam, const float* subln_w, const float* khalf) {
;     ...
;     for (int jj = 0; jj < NT; ++jj) {
;         const int j = NT - 1 - jj;
;         { const bool done = __all(qbound + sl2 * (float)(64 * j + 63 - qrow) < m - 24.f);
;           if (lane == 0) dflag[(jj & 1) * 8 + wid] = done ? 1 : 0; }
;         if (jj + 2 < NT) asm volatile("s_waitcnt vmcnt(8) lgkmcnt(0)\n\ts_barrier" ::: "memory"); else if (jj + 1 < NT) asm volatile("s_waitcnt vmcnt(4) lgkmcnt(0)\n\ts_barrier" ::: "memory"); else asm volatile("s_waitcnt vmcnt(0) lgkmcnt(0)\n\ts_barrier" ::: "memory");
;         { typedef int i32x4 __attribute__((ext_vector_type(4)));
;           const i32x4 fa = *(const LAS i32x4*)(lds + 4 * STG + (jj & 1) * 32), fb = *(const LAS i32x4*)(lds + 4 * STG + (jj & 1) * 32 + 16);
;           if (((fa[0] + fa[1]) + (fa[2] + fa[3])) + ((fb[0] + fb[1]) + (fb[2] + fb[3])) == 8) break; }
;         if (jj + 3 < NT) { DMA_TILE(j - 3, (stg + 3) & 3); }
;         const LAS unsigned char* kb = lds + stg * STG;
;         stg = (stg + 1) & 3;
.La_endB0:
	s_add_i32 s80, s80, 2
	s_and_b32 s80, s80, 3
	s_add_i32 s4, s59, s76
	s_add_i32 s81, s81, 2
	s_sub_i32 s76, s76, 0x80
	v_add_f32_e32 v137, 0xc3000000, v137
	s_cmp_eq_u32 s4, 0
	s_cbranch_scc1 .LBB0_420
	v_add_f32_e32 v243, v133, v121
	v_max_f32_e32 v243, 0xff7fffff, v243
	v_add_f32_e32 v243, 4.0, v243
	v_sub_f32_e32 v255, v255, v243

; __device__ __forceinline__ void unit(LAS unsigned char* lds, bf16_t* P1, const bf16_t* vaT, int b, int h, int qblk, float lam, const float* subln_w, const float* khalf) {
;     ...
;         { const bool done = __all(qbound + sl2 * (float)(64 * j + 63 - qrow) < m - 24.f);
;           if (lane == 0) dflag[(jj & 1) * 8 + wid] = done ? 1 : 0; }
;         if (jj + 2 < NT) asm volatile("s_waitcnt vmcnt(8) lgkmcnt(0)\n\ts_barrier" ::: "memory"); else if (jj + 1 < NT) asm volatile("s_waitcnt vmcnt(4) lgkmcnt(0)\n\ts_barrier" ::: "memory"); else asm volatile("s_waitcnt vmcnt(0) lgkmcnt(0)\n\ts_barrier" ::: "memory");
;         { typedef int i32x4 __attribute__((ext_vector_type(4)));
;           const i32x4 fa = *(const LAS i32x4*)(lds + 4 * STG + (jj & 1) * 32), fb = *(const LAS i32x4*)(lds + 4 * STG + (jj & 1) * 32 + 16);
;           if (((fa[0] + fa[1]) + (fa[2] + fa[3])) + ((fb[0] + fb[1]) + (fb[2] + fb[3])) == 8) break; }
;         if (jj + 3 < NT) { DMA_TILE(j - 3, (stg + 3) & 3); }
;         const LAS unsigned char* kb = lds + stg * STG;
;         stg = (stg + 1) & 3;
;         f32x16 S0, S1;
;         { float slv = sl2; asm volatile("" : "+v"(slv));
; #pragma unroll
;           for (int r = 0; r < 16; ++r) { S0[r] = __builtin_fmaf(slv, (float)((r & 3) + 8 * (r >> 2)), sl2h); S1[r] = S0[r]; } }
; #pragma unroll
;         for (int ks = 0; ks < 4; ++ks) {
;             const bf16x8 a0 = *(const LAS bf16x8*)(kb + koff[ks]);
;             const bf16x8 a1 = *(const LAS bf16x8*)(kb + koff[ks] + 32 * 256);
;             S0 = MFMA32(a0, qf[ks], S0); S1 = MFMA32(a1, qf[ks], S1);
;         }
;         const int kv0 = 64 * j;
;         if (j >= NT - 2) {
; #pragma unroll
;             for (int r = 0; r < 16; ++r) { const int kv = kv0 + crow(r, hi); if (kv > qrow) S0[r] = -INFINITY; if (kv + 32 > qrow) S1[r] = -INFINITY; }
;         }
;         const float tb0 = sl2 * (float)(kv0 - qrow), tb1 = tb0 + sl2 * 32.f;
;         float mx0 = S0[0], mx1 = S1[0];
; #pragma unroll
;         for (int r = 1; r < 16; ++r) { mx0 = fmaxf(mx0, S0[r]); mx1 = fmaxf(mx1, S1[r]); }
;         float mt = fmaxf(mx0 + tb0, mx1 + tb1); mt = fmaxf(mt, __shfl_xor(mt, 32));
;         const bool skip = __all((mt < m - 24.f) || (mt == -INFINITY));
;         if (!skip) {
;         const float mn = fmaxf(m, mt); const float alpha = ex2(m - mn); m = mn;
;         const float c0 = tb0 - mn, c1 = tb1 - mn;
.La_after_bar:
	s_lshl_b32 s82, s80, 15
	s_add_i32 s83, s82, 0x8000
	s_sub_i32 s100, s76, 64
	s_and_b32 s2, s81, 2
	s_lshl_b32 s2, s2, 4
	s_add_i32 s2, s2, 0x20000
	v_mov_b32_e32 v70, s2
	ds_read_b128 v[66:69], v70
	ds_read_b128 v[70:73], v70 offset:16
	v_add3_u32 v201, s82, v129, v151
	v_add3_u32 v135, s82, v185, v151
	v_add3_u32 v249, s82, v186, v151
	v_add3_u32 v254, s82, v187, v151
	ds_read_b128 v[192:195], v201
	ds_read_b128 v[202:205], v135
	ds_read_b128 v[210:213], v249
	ds_read_b128 v[218:221], v254
	ds_read_b128 v[196:199], v201 offset:8192
	ds_read_b128 v[206:209], v135 offset:8192
	ds_read_b128 v[214:217], v249 offset:8192
	ds_read_b128 v[222:225], v254 offset:8192
	s_waitcnt lgkmcnt(8)
	v_add3_u32 v66, v66, v67, v68
	v_add3_u32 v69, v69, v70, v71
	v_add_u32_e32 v72, v72, v73
	v_add3_u32 v66, v66, v69, v72
	v_cmp_eq_u32_e32 vcc, 8, v66
	s_cbranch_vccnz .LBB0_420
	s_add_i32 s5, s81, 2
	s_cmp_ge_u32 s5, s73
	s_cbranch_scc1 .La_qk_nodmaA
	s_add_i32 s5, s82, 0x10000
	s_and_b32 s5, s5, 0x18000
	s_add_i32 s5, s72, s5
	s_mov_b32 m0, s5
	s_waitcnt lgkmcnt(4)
	v_mfma_f32_32x32x16_bf16 v[82:97], v[192:195], v[98:101], v[226:241]
	global_load_lds_dwordx4 v[140:141], off
	s_add_i32 m0, s5, 0x400
	v_add_u32_e32 v244, s82, v168
	v_add_u32_e32 v245, s82, v169
	v_mfma_f32_32x32x16_bf16 v[82:97], v[202:205], v[102:105], v[82:97]
	global_load_lds_dwordx4 v[138:139], off
	s_add_i32 m0, s5, 0x4000
	v_add_u32_e32 v246, s82, v170
	v_add_u32_e32 v247, s82, v171
	v_mfma_f32_32x32x16_bf16 v[82:97], v[210:213], v[106:109], v[82:97]
	global_load_lds_dwordx4 v134, s[44:45]
	s_add_i32 m0, s5, 0x4400
	v_fma_f32 v255, v188, -2.0, v255
	v_mfma_f32_32x32x16_bf16 v[82:97], v[218:221], v[110:113], v[82:97]
	global_load_lds_dwordx4 v136, s[44:45]
	ds_read_b128 v[192:195], v244 offset:16384
	ds_read_b128 v[202:205], v244 offset:20480
	ds_read_b128 v[210:213], v244 offset:24576
	ds_read_b128 v[218:221], v244 offset:28672
	s_waitcnt lgkmcnt(4)
	v_mfma_f32_32x32x16_bf16 v[66:81], v[196:199], v[98:101], v[226:241]
	s_add_u32 s44, s44, 0xffffff80
	s_addc_u32 s45, s45, -1
	v_lshl_add_u64 v[138:139], v[138:139], 0, s[38:39]
	v_lshl_add_u64 v[140:141], v[140:141], 0, s[38:39]
	v_mfma_f32_32x32x16_bf16 v[66:81], v[206:209], v[102:105], v[66:81]
	v_exp_f32_e32 v82, v82
	v_exp_f32_e32 v83, v83
	v_mfma_f32_32x32x16_bf16 v[66:81], v[214:217], v[106:109], v[66:81]
	v_exp_f32_e32 v84, v84
	v_exp_f32_e32 v85, v85
	v_exp_f32_e32 v86, v86
	v_mfma_f32_32x32x16_bf16 v[66:81], v[222:225], v[110:113], v[66:81]
	v_exp_f32_e32 v87, v87
	v_exp_f32_e32 v88, v88
	v_exp_f32_e32 v89, v89
	v_cmp_le_f32_e32 vcc, 0, v255

; #define LAS __attribute__((address_space(3)))
; __device__ __forceinline__ int crow(int r, int hi) { return (r & 3) + 8 * (r >> 2) + 4 * hi; }
; __device__ __forceinline__ float ex2(float v) { return __builtin_amdgcn_exp2f(v); }
; #define MFMA32(a, b, c) __builtin_amdgcn_mfma_f32_32x32x16_bf16((a), (b), (c), 0, 0, 0)
; __device__ __forceinline__ void unit(LAS unsigned char* lds, bf16_t* P1, const bf16_t* vaT, int b, int h, int qblk, float lam, const float* subln_w, const float* khalf) {
;     ...
;         if (jj + 3 < NT) { DMA_TILE(j - 3, (stg + 3) & 3); }
;         const LAS unsigned char* kb = lds + stg * STG;
;         stg = (stg + 1) & 3;
;         f32x16 S0, S1;
;         { float slv = sl2; asm volatile("" : "+v"(slv));
; #pragma unroll
;           for (int r = 0; r < 16; ++r) { S0[r] = __builtin_fmaf(slv, (float)((r & 3) + 8 * (r >> 2)), sl2h); S1[r] = S0[r]; } }
; #pragma unroll
;         for (int ks = 0; ks < 4; ++ks) {
;             const bf16x8 a0 = *(const LAS bf16x8*)(kb + koff[ks]);
;             const bf16x8 a1 = *(const LAS bf16x8*)(kb + koff[ks] + 32 * 256);
;             S0 = MFMA32(a0, qf[ks], S0); S1 = MFMA32(a1, qf[ks], S1);
;         }
;         const int kv0 = 64 * j;
;         if (j >= NT - 2) {
; #pragma unroll
;             for (int r = 0; r < 16; ++r) { const int kv = kv0 + crow(r, hi); if (kv > qrow) S0[r] = -INFINITY; if (kv + 32 > qrow) S1[r] = -INFINITY; }
;         }
;         const float tb0 = sl2 * (float)(kv0 - qrow), tb1 = tb0 + sl2 * 32.f;
;         float mx0 = S0[0], mx1 = S1[0];
; #pragma unroll
;         for (int r = 1; r < 16; ++r) { mx0 = fmaxf(mx0, S0[r]); mx1 = fmaxf(mx1, S1[r]); }
;         float mt = fmaxf(mx0 + tb0, mx1 + tb1); mt = fmaxf(mt, __shfl_xor(mt, 32));
;         const bool skip = __all((mt < m - 24.f) || (mt == -INFINITY));
;         if (!skip) {
;         const float mn = fmaxf(m, mt); const float alpha = ex2(m - mn); m = mn;
;         const float c0 = tb0 - mn, c1 = tb1 - mn;
;         f32x2 ps2 = (f32x2){0.f, 0.f};
; #pragma unroll
;         for (int r = 0; r < 16; r += 2) { f32x2 a = (f32x2){S0[r], S0[r + 1]} + c0, bq = (f32x2){S1[r], S1[r + 1]} + c1;
;             a.x = ex2(a.x); a.y = ex2(a.y); bq.x = ex2(bq.x); bq.y = ex2(bq.y); S0[r] = a.x; S0[r + 1] = a.y; S1[r] = bq.x; S1[r + 1] = bq.y; ps2 = ps2 + a; ps2 = ps2 + bq; }
.La_endA:
	ds_read_b128 v[192:195], v201 offset:32768
	ds_read_b128 v[202:205], v135 offset:32768
	ds_read_b128 v[210:213], v249 offset:32768
	ds_read_b128 v[218:221], v254 offset:32768
	ds_read_b128 v[196:199], v201 offset:40960
	ds_read_b128 v[206:209], v135 offset:40960
	ds_read_b128 v[214:217], v249 offset:40960
	ds_read_b128 v[222:225], v254 offset:40960
	s_add_i32 s5, s81, 3
	s_cmp_ge_u32 s5, s73
	s_cbranch_scc1 .La_qk_nodmaB
	s_add_i32 s5, s82, 0x18000
	s_and_b32 s5, s5, 0x18000
	s_add_i32 s5, s72, s5
	s_mov_b32 m0, s5
	s_waitcnt lgkmcnt(4)
	v_mfma_f32_32x32x16_bf16 v[82:97], v[192:195], v[98:101], v[226:241]
	global_load_lds_dwordx4 v[140:141], off
	s_add_i32 m0, s5, 0x400
	v_fma_f32 v255, v188, -2.0, v255
	v_mfma_f32_32x32x16_bf16 v[82:97], v[202:205], v[102:105], v[82:97]
	global_load_lds_dwordx4 v[138:139], off
	s_add_i32 m0, s5, 0x4000
	v_mfma_f32_32x32x16_bf16 v[82:97], v[210:213], v[106:109], v[82:97]
	global_load_lds_dwordx4 v134, s[44:45]
	s_add_i32 m0, s5, 0x4400
	v_mfma_f32_32x32x16_bf16 v[82:97], v[218:221], v[110:113], v[82:97]
	global_load_lds_dwordx4 v136, s[44:45]
	ds_read_b128 v[192:195], v244 offset:49152
	ds_read_b128 v[202:205], v244 offset:53248
	ds_read_b128 v[210:213], v244 offset:57344
	ds_read_b128 v[218:221], v244 offset:61440
	s_waitcnt lgkmcnt(4)
	v_mfma_f32_32x32x16_bf16 v[66:81], v[196:199], v[98:101], v[226:241]
	s_add_u32 s44, s44, 0xffffff80
	s_addc_u32 s45, s45, -1
	v_lshl_add_u64 v[138:139], v[138:139], 0, s[38:39]
	v_lshl_add_u64 v[140:141], v[140:141], 0, s[38:39]
	v_mfma_f32_32x32x16_bf16 v[66:81], v[206:209], v[102:105], v[66:81]
	v_exp_f32_e32 v82, v82
	v_exp_f32_e32 v83, v83
	v_mfma_f32_32x32x16_bf16 v[66:81], v[214:217], v[106:109], v[66:81]
	v_exp_f32_e32 v84, v84
	v_exp_f32_e32 v85, v85
	v_exp_f32_e32 v86, v86
	v_mfma_f32_32x32x16_bf16 v[66:81], v[222:225], v[110:113], v[66:81]
	v_exp_f32_e32 v87, v87
	v_exp_f32_e32 v88, v88
	v_exp_f32_e32 v89, v89
	v_cmp_le_f32_e32 vcc, 0, v255

; #define LAS __attribute__((address_space(3)))
; __device__ __forceinline__ int crow(int r, int hi) { return (r & 3) + 8 * (r >> 2) + 4 * hi; }
; __device__ __forceinline__ float ex2(float v) { return __builtin_amdgcn_exp2f(v); }
; #define MFMA32(a, b, c) __builtin_amdgcn_mfma_f32_32x32x16_bf16((a), (b), (c), 0, 0, 0)
; __device__ __forceinline__ void unit(LAS unsigned char* lds, bf16_t* P1, const bf16_t* vaT, int b, int h, int qblk, float lam, const float* subln_w, const float* khalf) {
;     ...
;         for (int ks = 0; ks < 4; ++ks) {
;             const bf16x8 a0 = *(const LAS bf16x8*)(kb + koff[ks]);
;             const bf16x8 a1 = *(const LAS bf16x8*)(kb + koff[ks] + 32 * 256);
;             S0 = MFMA32(a0, qf[ks], S0); S1 = MFMA32(a1, qf[ks], S1);
;         }
;         const int kv0 = 64 * j;
;         if (j >= NT - 2) {
; #pragma unroll
;             for (int r = 0; r < 16; ++r) { const int kv = kv0 + crow(r, hi); if (kv > qrow) S0[r] = -INFINITY; if (kv + 32 > qrow) S1[r] = -INFINITY; }
;         }
;         const float tb0 = sl2 * (float)(kv0 - qrow), tb1 = tb0 + sl2 * 32.f;
;         float mx0 = S0[0], mx1 = S1[0];
; #pragma unroll
;         for (int r = 1; r < 16; ++r) { mx0 = fmaxf(mx0, S0[r]); mx1 = fmaxf(mx1, S1[r]); }
;         float mt = fmaxf(mx0 + tb0, mx1 + tb1); mt = fmaxf(mt, __shfl_xor(mt, 32));
;         const bool skip = __all((mt < m - 24.f) || (mt == -INFINITY));
;         if (!skip) {
;         const float mn = fmaxf(m, mt); const float alpha = ex2(m - mn); m = mn;
.La_qk_nodmaA:
	s_waitcnt lgkmcnt(4)
	v_mfma_f32_32x32x16_bf16 v[82:97], v[192:195], v[98:101], v[226:241]
	v_add_u32_e32 v244, s82, v168
	v_add_u32_e32 v245, s82, v169
	v_mfma_f32_32x32x16_bf16 v[82:97], v[202:205], v[102:105], v[82:97]
	v_add_u32_e32 v246, s82, v170
	v_add_u32_e32 v247, s82, v171
	v_mfma_f32_32x32x16_bf16 v[82:97], v[210:213], v[106:109], v[82:97]
	v_fma_f32 v255, v188, -2.0, v255
	v_mfma_f32_32x32x16_bf16 v[82:97], v[218:221], v[110:113], v[82:97]
	ds_read_b128 v[192:195], v244 offset:16384
	ds_read_b128 v[202:205], v244 offset:20480
	ds_read_b128 v[210:213], v244 offset:24576
	ds_read_b128 v[218:221], v244 offset:28672
	s_waitcnt lgkmcnt(4)
	v_mfma_f32_32x32x16_bf16 v[66:81], v[196:199], v[98:101], v[226:241]
	v_mfma_f32_32x32x16_bf16 v[66:81], v[206:209], v[102:105], v[66:81]
	v_exp_f32_e32 v82, v82
	v_exp_f32_e32 v83, v83
	v_mfma_f32_32x32x16_bf16 v[66:81], v[214:217], v[106:109], v[66:81]
	v_exp_f32_e32 v84, v84
	v_exp_f32_e32 v85, v85
	v_exp_f32_e32 v86, v86
	v_mfma_f32_32x32x16_bf16 v[66:81], v[222:225], v[110:113], v[66:81]
	v_exp_f32_e32 v87, v87
	v_exp_f32_e32 v88, v88
	v_exp_f32_e32 v89, v89
	v_cmp_le_f32_e32 vcc, 0, v255
	s_branch .La_qk_doneA
.La_maxA:
	v_max3_f32 v0, v82, v83, v84
	v_max3_f32 v0, v0, v85, v86
	v_max3_f32 v0, v0, v87, v88
	v_max_f32_e32 v0, v0, v89
	v_log_f32_e32 v0, v0
	v_add_f32_e32 v143, v133, v121
	v_max_f32_e32 v143, 0xff7fffff, v143
	v_max3_f32 v0, v0, v90, v91
	v_max3_f32 v0, v0, v92, v93
	v_max3_f32 v0, v0, v94, v95
	v_max3_f32 v0, v0, v96, v97
	s_nop 1
	v_max3_f32 v120, v66, v67, v68
	v_max3_f32 v120, v120, v69, v70
	v_max3_f32 v120, v120, v71, v72
	v_max3_f32 v120, v120, v73, v74
	v_max3_f32 v120, v120, v75, v76
	v_max3_f32 v120, v120, v77, v78
	v_max3_f32 v120, v120, v79, v80
	v_max_f32_e32 v120, v120, v81
	v_add_f32_e32 v120, v188, v120
	v_max_f32_e32 v0, v0, v120
	v_add_f32_e32 v0, v132, v0
	v_mov_b32_e32 v120, v0
	s_nop 1
	v_permlane32_swap_b32_e32 v0, v120
	v_max_f32_e32 v0, v0, v120
	v_cmp_lt_f32_e32 vcc, v0, v143
	v_max_f32_e32 v133, v133, v0
	v_add_f32_e32 v243, v133, v121
	v_max_f32_e32 v243, 0xff7fffff, v243
	v_add_f32_e32 v243, 4.0, v243
	v_sub_f32_e32 v255, v0, v243
	s_andn2_b64 s[2:3], exec, vcc
	s_cbranch_scc0 .La_skipA
	s_branch .La_nomaxA

; #define LAS __attribute__((address_space(3)))
; __device__ __forceinline__ int crow(int r, int hi) { return (r & 3) + 8 * (r >> 2) + 4 * hi; }
; __device__ __forceinline__ float ex2(float v) { return __builtin_amdgcn_exp2f(v); }
; #define MFMA32(a, b, c) __builtin_amdgcn_mfma_f32_32x32x16_bf16((a), (b), (c), 0, 0, 0)
; __device__ __forceinline__ void unit(LAS unsigned char* lds, bf16_t* P1, const bf16_t* vaT, int b, int h, int qblk, float lam, const float* subln_w, const float* khalf) {
;     ...
;         for (int ks = 0; ks < 4; ++ks) {
;             const bf16x8 a0 = *(const LAS bf16x8*)(kb + koff[ks]);
;             const bf16x8 a1 = *(const LAS bf16x8*)(kb + koff[ks] + 32 * 256);
;             S0 = MFMA32(a0, qf[ks], S0); S1 = MFMA32(a1, qf[ks], S1);
;         }
;         const int kv0 = 64 * j;
;         if (j >= NT - 2) {
; #pragma unroll
;             for (int r = 0; r < 16; ++r) { const int kv = kv0 + crow(r, hi); if (kv > qrow) S0[r] = -INFINITY; if (kv + 32 > qrow) S1[r] = -INFINITY; }
;         }
;         const float tb0 = sl2 * (float)(kv0 - qrow), tb1 = tb0 + sl2 * 32.f;
;         float mx0 = S0[0], mx1 = S1[0];
; #pragma unroll
;         for (int r = 1; r < 16; ++r) { mx0 = fmaxf(mx0, S0[r]); mx1 = fmaxf(mx1, S1[r]); }
;         float mt = fmaxf(mx0 + tb0, mx1 + tb1); mt = fmaxf(mt, __shfl_xor(mt, 32));
;         const bool skip = __all((mt < m - 24.f) || (mt == -INFINITY));
;         if (!skip) {
;         const float mn = fmaxf(m, mt); const float alpha = ex2(m - mn); m = mn;
;         const float c0 = tb0 - mn, c1 = tb1 - mn;
;         f32x2 ps2 = (f32x2){0.f, 0.f};
; #pragma unroll
;         for (int r = 0; r < 16; r += 2) { f32x2 a = (f32x2){S0[r], S0[r + 1]} + c0, bq = (f32x2){S1[r], S1[r + 1]} + c1;
;             a.x = ex2(a.x); a.y = ex2(a.y); bq.x = ex2(bq.x); bq.y = ex2(bq.y); S0[r] = a.x; S0[r + 1] = a.y; S1[r] = bq.x; S1[r + 1] = bq.y; ps2 = ps2 + a; ps2 = ps2 + bq; }
.La_qk_nodmaB:
	s_waitcnt lgkmcnt(4)
	v_mfma_f32_32x32x16_bf16 v[82:97], v[192:195], v[98:101], v[226:241]
	v_fma_f32 v255, v188, -2.0, v255
	v_mfma_f32_32x32x16_bf16 v[82:97], v[202:205], v[102:105], v[82:97]
	v_mfma_f32_32x32x16_bf16 v[82:97], v[210:213], v[106:109], v[82:97]
	v_mfma_f32_32x32x16_bf16 v[82:97], v[218:221], v[110:113], v[82:97]
	ds_read_b128 v[192:195], v244 offset:49152
	ds_read_b128 v[202:205], v244 offset:53248
	ds_read_b128 v[210:213], v244 offset:57344
	ds_read_b128 v[218:221], v244 offset:61440
	s_waitcnt lgkmcnt(4)
	v_mfma_f32_32x32x16_bf16 v[66:81], v[196:199], v[98:101], v[226:241]
	v_mfma_f32_32x32x16_bf16 v[66:81], v[206:209], v[102:105], v[66:81]
	v_exp_f32_e32 v82, v82
	v_exp_f32_e32 v83, v83
	v_mfma_f32_32x32x16_bf16 v[66:81], v[214:217], v[106:109], v[66:81]
	v_exp_f32_e32 v84, v84
	v_exp_f32_e32 v85, v85
	v_exp_f32_e32 v86, v86
	v_mfma_f32_32x32x16_bf16 v[66:81], v[222:225], v[110:113], v[66:81]
	v_exp_f32_e32 v87, v87
	v_exp_f32_e32 v88, v88
	v_exp_f32_e32 v89, v89
	v_cmp_le_f32_e32 vcc, 0, v255
	s_branch .La_qk_doneB
